# v28 + grid-barrier spin loops back off with s_sleep 3 (less polling traffic)
# speedup vs baseline: 1.0022x; 1.0015x over previous
; __global__ void __launch_bounds__(512, 2) mega(Params p) {
;     ...
;     grid.sync();
.LBB0_72:
	s_sleep 3
	global_load_dword v2, v0, s[10:11] offset:32 sc1
	s_waitcnt vmcnt(0)
	v_and_b32_e32 v2, 0xffff0000, v2
	v_cmp_ne_u32_e32 vcc, v2, v1
	s_or_b64 s[4:5], vcc, s[4:5]
	s_andn2_b64 exec, exec, s[4:5]
	s_cbranch_execnz .LBB0_72

; DI unsigned xb_ld(unsigned* p)              { return __hip_atomic_load(p, __ATOMIC_RELAXED, __HIP_MEMORY_SCOPE_AGENT); }
; DI void xcd_barrier_complete(unsigned* bar, unsigned x, unsigned& nloc, unsigned& nx) {
;     const unsigned G = gridDim.x * gridDim.y * gridDim.z;
;     unsigned sum, cnt, mine, sp = 0u;
;     for (;;) {
;         sum = 0u; cnt = 0u; mine = 0u;
; #pragma unroll
;         for (unsigned j = 0; j < 16; ++j) { const unsigned c = xb_ld(&bar[XB_XCNT(j)]); sum += c; cnt += (c > 0u) ? 1u : 0u; mine = (j == x) ? c : mine; }
;         if (sum == G) break;
;         __builtin_amdgcn_s_sleep(1);
;         if ((++sp & 255u) == 0u) { if (xb_ld(&bar[XB_TMO])) break; if (sp > XB_SPIN_CAP) { atomicAdd(&bar[XB_TMO], 1u); break; } }
;     }
;     nloc = mine > 0u ? mine : 1u; nx = cnt > 0u ? cnt : 1u;
; }
.LBB0_108:
	v_readlane_b32 s6, v255, 7
	v_readlane_b32 s7, v255, 8
	s_waitcnt lgkmcnt(0)
	global_load_dword v0, v213, s[72:73] sc1
	s_nop 2
	global_load_dword v1, v213, s[6:7] sc1
	global_load_dword v2, v213, s[92:93] sc1
	global_load_dword v3, v213, s[94:95] sc1
	v_readlane_b32 s6, v253, 8
	v_readlane_b32 s7, v253, 9
	v_readlane_b32 s14, v253, 7
	s_waitcnt vmcnt(2)
	v_add_u32_e32 v16, v1, v0
	s_nop 1
	global_load_dword v4, v213, s[6:7] sc1
	v_readlane_b32 s6, v253, 10
	v_readlane_b32 s7, v253, 11
	s_waitcnt vmcnt(2)
	v_add_u32_e32 v16, v16, v2
	s_waitcnt vmcnt(1)
	v_add_u32_e32 v16, v16, v3
	s_waitcnt vmcnt(0)
	v_add_u32_e32 v16, v16, v4
	global_load_dword v5, v213, s[6:7] sc1
	v_readlane_b32 s6, v253, 12
	v_readlane_b32 s7, v253, 13
	s_waitcnt vmcnt(0)
	v_add_u32_e32 v16, v16, v5
	s_nop 2
	global_load_dword v6, v213, s[6:7] sc1
	v_readlane_b32 s6, v253, 14
	v_readlane_b32 s7, v253, 15
	s_waitcnt vmcnt(0)
	v_add_u32_e32 v16, v16, v6
	s_nop 2
	global_load_dword v7, v213, s[6:7] sc1
	v_readlane_b32 s6, v253, 16
	v_readlane_b32 s7, v253, 17
	s_waitcnt vmcnt(0)
	v_add_u32_e32 v16, v16, v7
	s_nop 2
	global_load_dword v8, v213, s[6:7] sc1
	v_readlane_b32 s6, v253, 18
	v_readlane_b32 s7, v253, 19
	s_waitcnt vmcnt(0)
	v_add_u32_e32 v16, v16, v8
	s_nop 2
	global_load_dword v9, v213, s[6:7] sc1
	v_readlane_b32 s6, v253, 20
	v_readlane_b32 s7, v253, 21
	s_waitcnt vmcnt(0)
	v_add_u32_e32 v16, v16, v9
	s_nop 2
	global_load_dword v10, v213, s[6:7] sc1
	v_readlane_b32 s6, v253, 22
	v_readlane_b32 s7, v253, 23
	s_waitcnt vmcnt(0)
	v_add_u32_e32 v16, v16, v10
	s_nop 2
	global_load_dword v11, v213, s[6:7] sc1
	v_readlane_b32 s6, v253, 24
	v_readlane_b32 s7, v253, 25
	s_waitcnt vmcnt(0)
	v_add_u32_e32 v16, v16, v11
	s_nop 2
	global_load_dword v12, v213, s[6:7] sc1
	v_readlane_b32 s6, v253, 26
	v_readlane_b32 s7, v253, 27
	s_waitcnt vmcnt(0)
	v_add_u32_e32 v16, v16, v12
	s_nop 2
	global_load_dword v13, v213, s[6:7] sc1
	v_readlane_b32 s6, v253, 28
	v_readlane_b32 s7, v253, 29
	s_waitcnt vmcnt(0)
	v_add_u32_e32 v16, v16, v13
	s_nop 2
	global_load_dword v14, v213, s[6:7] sc1
	v_readlane_b32 s6, v253, 30
	v_readlane_b32 s7, v253, 31
	s_waitcnt vmcnt(0)
	v_add_u32_e32 v16, v16, v14
	s_nop 2
	global_load_dword v15, v213, s[6:7] sc1
	s_mov_b64 s[6:7], -1
	s_waitcnt vmcnt(0)
	v_add_u32_e32 v16, v16, v15
	v_cmp_eq_u32_e32 vcc, s14, v16
	s_mov_b64 s[14:15], -1
	s_cbranch_vccnz .LBB0_107
	s_and_b32 s6, s22, 0xff
	s_cmp_eq_u32 s6, 0
	s_mov_b64 s[6:7], -1
	s_mov_b64 s[18:19], -1
	s_sleep 3
	s_cbranch_scc0 .LBB0_112
	global_load_dword v16, v213, s[86:87] sc1
	s_waitcnt vmcnt(0)
	v_cmp_eq_u32_e32 vcc, 0, v16
	s_cbranch_vccnz .LBB0_114
	s_mov_b64 s[18:19], 0

; DI unsigned xb_ld(unsigned* p)              { return __hip_atomic_load(p, __ATOMIC_RELAXED, __HIP_MEMORY_SCOPE_AGENT); }
; DI unsigned xb_add(unsigned* p, unsigned v) { return __hip_atomic_fetch_add(p, v, __ATOMIC_RELAXED, __HIP_MEMORY_SCOPE_AGENT); }
; #define XB_SPIN(cond, bar) do { unsigned _sp = 0; while (cond) { __builtin_amdgcn_s_sleep(1); \
;     if ((++_sp & 255u) == 0u) { if (xb_ld(&(bar)[XB_TMO])) break; if (_sp > XB_SPIN_CAP) { atomicAdd(&(bar)[XB_TMO], 1u); break; } } } } while (0)
; DI void xcd_barrier(const XcdBarrier& b) {
;     ...
;             const unsigned og = xb_add(&bar[XB_TOP], 1u);
;             const unsigned tg = og / nx;
;             if (og + 1u == (tg + 1u) * nx) xb_add(&bar[XB_TOPGEN], 1u);
;             else XB_SPIN(xb_ld(&bar[XB_TOPGEN]) == tg, bar);
;             __builtin_amdgcn_fence(__ATOMIC_ACQUIRE, "agent");
;             xb_add(&bar[XB_XGEN(b.x)], 1u);
;             asm volatile("s_waitcnt vmcnt(0)" ::: "memory");
;         } else {
;             XB_SPIN(xb_ld(&bar[XB_XGEN(b.x)]) == gen, bar);
.LBB0_126:
	s_and_b32 s30, s38, 0xff
	s_mov_b64 s[26:27], -1
	s_cmp_lg_u32 s30, 0
	s_mov_b64 s[36:37], -1
	s_sleep 3
	s_cbranch_scc1 .LBB0_129
	global_load_dword v0, v213, s[86:87] sc1
	s_waitcnt vmcnt(0)
	v_cmp_eq_u32_e32 vcc, 0, v0
	s_cbranch_vccnz .LBB0_131
	s_mov_b64 s[36:37], 0
	s_mov_b64 s[30:31], -1
